# lever 1/2: mem-attention loop PV section de-serialised: 12 ds_read->lgkmcnt(0)->MFMA steps now a 7-deep fragment ring in spare VGPRs with counted waits
# speedup vs baseline: 1.0100x; 1.0100x over previous
.LBB0_923:
	s_mul_i32 s21, s40, 0x4400
	v_add_u32_e32 v176, s21, v179
	v_exp_f32_e32 v173, v162
	v_exp_f32_e32 v162, v86
	v_exp_f32_e32 v86, v68
	v_add_u32_e32 v68, 0x8800, v176
	v_exp_f32_e32 v175, v164
	v_exp_f32_e32 v93, v165
	v_exp_f32_e32 v95, v166
	v_exp_f32_e32 v79, v167
	ds_read2_b64 v[164:167], v68 offset1:2
	v_exp_f32_e32 v91, v163
	v_exp_f32_e32 v172, v80
	v_exp_f32_e32 v90, v81
	v_exp_f32_e32 v94, v84
	v_exp_f32_e32 v78, v85
	v_exp_f32_e32 v92, v83
	v_exp_f32_e32 v163, v168
	v_exp_f32_e32 v83, v169
	v_exp_f32_e32 v85, v170
	v_exp_f32_e32 v77, v171
	v_cvt_pk_bf16_f32 v168, v173, v91
	v_cvt_pk_bf16_f32 v169, v172, v90
	v_cvt_pk_bf16_f32 v170, v95, v79
	v_cvt_pk_bf16_f32 v171, v94, v78
	ds_read2_b64 v[192:195], v68 offset0:4 offset1:6
	v_exp_f32_e32 v174, v82
	s_waitcnt lgkmcnt(1)
	v_mfma_f32_32x32x16_bf16 v[48:63], v[164:167], v[168:171], v[48:63]
	v_exp_f32_e32 v82, v87
	v_exp_f32_e32 v87, v88
	v_exp_f32_e32 v81, v89
	v_exp_f32_e32 v84, v72
	v_exp_f32_e32 v76, v73
	v_exp_f32_e32 v89, v74
	v_exp_f32_e32 v73, v75
	v_exp_f32_e32 v88, v70
	v_exp_f32_e32 v72, v71
	v_cvt_pk_bf16_f32 v164, v85, v77
	v_cvt_pk_bf16_f32 v165, v84, v76
	v_cvt_pk_bf16_f32 v166, v89, v73
	v_cvt_pk_bf16_f32 v167, v88, v72
	ds_read2_b64 v[196:199], v68 offset0:8 offset1:10
	ds_read2_b64 v[200:203], v68 offset0:12 offset1:14
	s_waitcnt lgkmcnt(2)
	v_mfma_f32_32x32x16_bf16 v[48:63], v[192:195], v[164:167], v[48:63]
	v_cvt_pk_bf16_f32 v192, v175, v93
	v_cvt_pk_bf16_f32 v193, v174, v92
	v_cvt_pk_bf16_f32 v194, v163, v83
	v_cvt_pk_bf16_f32 v195, v162, v82
	v_exp_f32_e32 v80, v69
	v_exp_f32_e32 v69, v64
	v_exp_f32_e32 v65, v65
	s_waitcnt lgkmcnt(1)
	v_mfma_f32_32x32x16_bf16 v[48:63], v[196:199], v[192:195], v[48:63]
	v_exp_f32_e32 v68, v66
	v_exp_f32_e32 v64, v67
	v_cvt_pk_bf16_f32 v196, v87, v81
	v_cvt_pk_bf16_f32 v197, v86, v80
	v_cvt_pk_bf16_f32 v198, v69, v65
	v_cvt_pk_bf16_f32 v199, v68, v64
	v_add_u32_e32 v66, 0x9800, v176
	s_xor_b32 s21, s38, 1
	v_add_u32_e32 v241, 0xa800, v176
	v_add_u32_e32 v242, 0xb800, v176
	ds_read2_b64 v[216:219], v66 offset0:32 offset1:34
	ds_read2_b64 v[220:223], v66 offset0:36 offset1:38
	ds_read2_b64 v[224:227], v66 offset0:40 offset1:42
	ds_read2_b64 v[228:231], v66 offset0:44 offset1:46
	ds_read2_b64 v[232:235], v241 offset0:64 offset1:66
	ds_read2_b64 v[236:239], v241 offset0:68 offset1:70
	s_waitcnt lgkmcnt(6)
	v_mfma_f32_32x32x16_bf16 v[48:63], v[200:203], v[196:199], v[48:63]
	ds_read2_b64 v[200:203], v241 offset0:72 offset1:74
	s_mulk_i32 s21, 0x4400
	s_add_i32 s21, s21, 0
	s_waitcnt lgkmcnt(6)
	v_mfma_f32_32x32x16_bf16 v[32:47], v[216:219], v[168:171], v[32:47]
	ds_read2_b64 v[216:219], v241 offset0:76 offset1:78
	s_waitcnt lgkmcnt(6)
	v_mfma_f32_32x32x16_bf16 v[32:47], v[220:223], v[164:167], v[32:47]
	ds_read2_b64 v[220:223], v242 offset0:96 offset1:98
	s_waitcnt lgkmcnt(6)
	v_mfma_f32_32x32x16_bf16 v[32:47], v[224:227], v[192:195], v[32:47]
	ds_read2_b64 v[224:227], v242 offset0:100 offset1:102
	s_waitcnt lgkmcnt(6)
	v_mfma_f32_32x32x16_bf16 v[32:47], v[228:231], v[196:199], v[32:47]
	ds_read2_b64 v[228:231], v242 offset0:104 offset1:106
	s_waitcnt lgkmcnt(6)
	v_mfma_f32_32x32x16_bf16 v[16:31], v[232:235], v[168:171], v[16:31]
	ds_read2_b64 v[232:235], v242 offset0:108 offset1:110
	s_waitcnt lgkmcnt(6)
	v_mfma_f32_32x32x16_bf16 v[16:31], v[236:239], v[164:167], v[16:31]
	s_waitcnt lgkmcnt(5)
	v_mfma_f32_32x32x16_bf16 v[16:31], v[200:203], v[192:195], v[16:31]
	s_waitcnt lgkmcnt(4)
	v_mfma_f32_32x32x16_bf16 v[16:31], v[216:219], v[196:199], v[16:31]
	s_waitcnt lgkmcnt(3)
	v_mfma_f32_32x32x16_bf16 v[0:15], v[220:223], v[168:171], v[0:15]
	s_waitcnt lgkmcnt(2)
	v_mfma_f32_32x32x16_bf16 v[0:15], v[224:227], v[164:167], v[0:15]
	s_waitcnt lgkmcnt(1)
	v_mfma_f32_32x32x16_bf16 v[0:15], v[228:231], v[192:195], v[0:15]
	s_waitcnt lgkmcnt(0)
	v_mfma_f32_32x32x16_bf16 v[0:15], v[232:235], v[196:199], v[0:15]
	s_and_saveexec_b64 s[36:37], s[6:7]
	s_cbranch_execz .LBB0_925
	v_add3_u32 v66, s21, v190, v191
	s_waitcnt vmcnt(2)
	ds_write_b128 v66, v[128:131]
